# P10 g_final loads batched only (work5)
# baseline (speedup 1.0000x reference)
.LBB0_2180:
	s_or_b64 exec, exec, s[6:7]
	global_load_dwordx4 v[120:123], v[68:69], off
	global_load_dwordx4 v[124:127], v[70:71], off
	global_load_dwordx4 v[128:131], v[72:73], off
	global_load_dwordx4 v[132:135], v[74:75], off
	global_load_dwordx4 v[136:139], v[76:77], off
	global_load_dwordx4 v[140:143], v[78:79], off
	global_load_dwordx4 v[144:147], v[80:81], off
	global_load_dwordx4 v[148:151], v[82:83], off
	s_waitcnt vmcnt(15)
	v_mul_f32_e32 v32, v29, v29
	s_waitcnt vmcnt(14)
	v_mul_f32_e32 v33, v25, v25
	v_fmac_f32_e32 v32, v28, v28
	v_fmac_f32_e32 v33, v24, v24
	v_fmac_f32_e32 v32, v30, v30
	v_fmac_f32_e32 v33, v26, v26
	v_fmac_f32_e32 v32, v31, v31
	v_fmac_f32_e32 v33, v27, v27
	v_add_f32_e32 v32, v32, v33
	s_waitcnt vmcnt(13)
	v_mul_f32_e32 v33, v21, v21
	v_fmac_f32_e32 v33, v20, v20
	v_fmac_f32_e32 v33, v22, v22
	v_fmac_f32_e32 v33, v23, v23
	v_add_f32_e32 v36, v32, v33
	s_waitcnt vmcnt(12)
	v_mul_f32_e32 v37, v17, v17
	v_fmac_f32_e32 v37, v16, v16
	v_fmac_f32_e32 v37, v18, v18
	v_fmac_f32_e32 v37, v19, v19
	s_waitcnt vmcnt(11)
	v_mov_b32_e32 v38, v13
	s_waitcnt vmcnt(10)
	v_mov_b32_e32 v39, v9
	v_add_f32_e32 v40, v36, v37
	v_mov_b32_e32 v36, v12
	v_mov_b32_e32 v37, v8
	v_pk_mul_f32 v[38:39], v[38:39], v[38:39]
	v_add_u32_e32 v56, s18, v56
	v_pk_fma_f32 v[36:37], v[36:37], v[36:37], v[38:39]
	v_mov_b32_e32 v38, v14
	v_mov_b32_e32 v39, v10
	v_pk_fma_f32 v[36:37], v[38:39], v[38:39], v[36:37]
	v_mov_b32_e32 v38, v15
	v_mov_b32_e32 v39, v11
	v_pk_fma_f32 v[36:37], v[38:39], v[38:39], v[36:37]
	s_waitcnt vmcnt(9)
	v_mov_b32_e32 v38, v5
	v_add_f32_e32 v36, v40, v36
	s_waitcnt vmcnt(8)
	v_mov_b32_e32 v39, v1
	v_add_f32_e32 v40, v36, v37
	v_mov_b32_e32 v36, v4
	v_mov_b32_e32 v37, v0
	v_pk_mul_f32 v[38:39], v[38:39], v[38:39]
	v_lshl_add_u64 v[86:87], v[86:87], 0, s[0:1]
	v_pk_fma_f32 v[36:37], v[36:37], v[36:37], v[38:39]
	v_mov_b32_e32 v38, v6
	v_mov_b32_e32 v39, v2
	v_pk_fma_f32 v[36:37], v[38:39], v[38:39], v[36:37]
	v_mov_b32_e32 v38, v7
	v_mov_b32_e32 v39, v3
	v_pk_fma_f32 v[36:37], v[38:39], v[38:39], v[36:37]
	v_lshl_add_u64 v[88:89], v[88:89], 0, s[0:1]
	v_add_f32_e32 v36, v40, v36
	v_add_f32_e32 v36, v36, v37
	ds_bpermute_b32 v37, v246, v36
	s_waitcnt lgkmcnt(0)
	v_add_f32_e32 v36, v36, v37
	ds_bpermute_b32 v37, v247, v36
	s_waitcnt lgkmcnt(0)
	v_add_f32_e32 v36, v36, v37
	ds_bpermute_b32 v37, v248, v36
	s_waitcnt lgkmcnt(0)
	v_add_f32_e32 v36, v36, v37
	ds_bpermute_b32 v37, v249, v36
	s_waitcnt lgkmcnt(0)
	v_add_f32_e32 v36, v36, v37
	ds_bpermute_b32 v37, v251, v36
	s_waitcnt lgkmcnt(0)
	v_add_f32_e32 v36, v36, v37
	ds_bpermute_b32 v37, v252, v36
	s_waitcnt lgkmcnt(0)
	v_add_f32_e32 v36, v36, v37
	v_fmamk_f32 v36, v36, 0x3a000000, v116
	v_mul_f32_e32 v37, 0x4b800000, v36
	v_cmp_gt_f32_e32 vcc, s14, v36
	s_nop 1
	v_cndmask_b32_e32 v36, v36, v37, vcc
	v_rsq_f32_e32 v36, v36
	s_nop 0
	v_mul_f32_e32 v37, 0x45800000, v36
	v_cndmask_b32_e32 v36, v36, v37, vcc
	v_pk_mul_f32 v[28:29], v[36:37], v[28:29] op_sel_hi:[0,1]
	v_pk_mul_f32 v[30:31], v[36:37], v[30:31] op_sel_hi:[0,1]
	s_waitcnt vmcnt(7)
	v_pk_mul_f32 v[30:31], v[30:31], v[122:123]
	v_pk_mul_f32 v[28:29], v[28:29], v[120:121]
	global_store_dwordx4 v[106:107], v[28:31], off
	v_pk_mul_f32 v[26:27], v[36:37], v[26:27] op_sel_hi:[0,1]
	v_pk_mul_f32 v[24:25], v[36:37], v[24:25] op_sel_hi:[0,1]
	v_pk_mul_f32 v[22:23], v[36:37], v[22:23] op_sel_hi:[0,1]
	v_pk_mul_f32 v[20:21], v[36:37], v[20:21] op_sel_hi:[0,1]
	v_pk_mul_f32 v[18:19], v[36:37], v[18:19] op_sel_hi:[0,1]
	v_pk_mul_f32 v[16:17], v[36:37], v[16:17] op_sel_hi:[0,1]
	v_pk_mul_f32 v[14:15], v[36:37], v[14:15] op_sel_hi:[0,1]
	v_pk_mul_f32 v[12:13], v[36:37], v[12:13] op_sel_hi:[0,1]
	v_pk_mul_f32 v[10:11], v[36:37], v[10:11] op_sel_hi:[0,1]
	v_pk_mul_f32 v[8:9], v[36:37], v[8:9] op_sel_hi:[0,1]
	v_pk_mul_f32 v[6:7], v[36:37], v[6:7] op_sel_hi:[0,1]
	v_pk_mul_f32 v[4:5], v[36:37], v[4:5] op_sel_hi:[0,1]
	v_pk_mul_f32 v[2:3], v[36:37], v[2:3] op_sel_hi:[0,1]
	v_pk_mul_f32 v[0:1], v[36:37], v[0:1] op_sel_hi:[0,1]
	s_waitcnt vmcnt(7)
	v_pk_mul_f32 v[24:25], v[24:25], v[124:125]
	v_pk_mul_f32 v[26:27], v[26:27], v[126:127]
	global_store_dwordx4 v[106:107], v[24:27], off offset:1024
	s_waitcnt vmcnt(7)
	v_pk_mul_f32 v[20:21], v[20:21], v[128:129]
	v_pk_mul_f32 v[22:23], v[22:23], v[130:131]
	global_store_dwordx4 v[106:107], v[20:23], off offset:2048
	s_waitcnt vmcnt(7)
	v_pk_mul_f32 v[16:17], v[16:17], v[132:133]
	v_pk_mul_f32 v[18:19], v[18:19], v[134:135]
	global_store_dwordx4 v[106:107], v[16:19], off offset:3072
	v_add_co_u32_e32 v20, vcc, s9, v106
	s_waitcnt vmcnt(7)
	v_pk_mul_f32 v[12:13], v[12:13], v[136:137]
	v_addc_co_u32_e32 v21, vcc, 0, v107, vcc
	v_pk_mul_f32 v[14:15], v[14:15], v[138:139]
	global_store_dwordx4 v[20:21], v[12:15], off
	s_waitcnt vmcnt(7)
	v_pk_mul_f32 v[8:9], v[8:9], v[140:141]
	v_pk_mul_f32 v[10:11], v[10:11], v[142:143]
	global_store_dwordx4 v[20:21], v[8:11], off offset:1024
	s_waitcnt vmcnt(7)
	v_pk_mul_f32 v[4:5], v[4:5], v[144:145]
	v_pk_mul_f32 v[6:7], v[6:7], v[146:147]
	global_store_dwordx4 v[20:21], v[4:7], off offset:2048
	v_add_u32_e32 v8, 0x2000, v56
	v_cmp_lt_i32_e32 vcc, s15, v8
	s_or_b64 s[2:3], vcc, s[2:3]
	s_waitcnt vmcnt(7)
	v_pk_mul_f32 v[0:1], v[0:1], v[148:149]
	v_pk_mul_f32 v[2:3], v[2:3], v[150:151]
	global_store_dwordx4 v[20:21], v[0:3], off offset:3072
	s_andn2_b64 exec, exec, s[2:3]
	s_cbranch_execz .LBB0_2185
